# K-loops P1/P4: counter/address advance/exit test moved from behind the loop-back barrier into the last MFMA block
# baseline (speedup 1.0000x reference)
.LBB0_165:
	ds_read_b128 v[114:117], v177
	ds_read_b128 v[118:121], v177 offset:1024
	ds_read_b128 v[122:125], v177 offset:2048
	ds_read_b128 v[126:129], v177 offset:3072
	ds_read_b128 v[182:185], v178
	ds_read_b128 v[186:189], v178 offset:1024
	ds_read_b128 v[190:193], v178 offset:2048
	ds_read_b128 v[194:197], v178 offset:3072
	s_add_u32 s0, s70, 0xfff80080
	s_addc_u32 s1, s71, -1
	s_cmp_eq_u32 s76, 28
	s_cselect_b32 s13, s9, s1
	s_cselect_b32 s12, s61, s0
	s_cselect_b32 s1, s63, s21
	s_cselect_b32 s0, s75, s20
	v_lshl_add_u64 v[174:175], s[70:71], 0, v[166:167]
	s_add_i32 m0, s35, 0xc000
	ds_read_b128 v[198:201], v179
	ds_read_b128 v[202:205], v179 offset:1024
	ds_read_b128 v[206:209], v179 offset:2048
	ds_read_b128 v[210:213], v179 offset:3072
	ds_read_b128 v[214:217], v179 offset:4096
	ds_read_b128 v[218:221], v179 offset:5120
	ds_read_b128 v[222:225], v179 offset:6144
	ds_read_b128 v[226:229], v179 offset:7168
	global_load_lds_dwordx4 v[174:175], off
	v_lshl_add_u64 v[174:175], s[70:71], 0, v[168:169]
	s_add_i32 m0, s35, 0xe000
	s_nop 0
	global_load_lds_dwordx4 v[174:175], off
	s_waitcnt vmcnt(8)
	s_waitcnt lgkmcnt(0)
	s_barrier
	s_setprio 1
	s_waitcnt lgkmcnt(0)
	v_mfma_f32_16x16x32_bf16 v[142:145], v[114:117], v[198:201], v[142:145]
	v_mfma_f32_16x16x32_bf16 v[138:141], v[122:125], v[198:201], v[138:141]
	v_mfma_f32_16x16x32_bf16 v[110:113], v[114:117], v[206:209], v[110:113]
	v_mfma_f32_16x16x32_bf16 v[106:109], v[122:125], v[206:209], v[106:109]
	v_mfma_f32_16x16x32_bf16 v[94:97], v[114:117], v[214:217], v[94:97]
	v_mfma_f32_16x16x32_bf16 v[90:93], v[122:125], v[214:217], v[90:93]
	v_mfma_f32_16x16x32_bf16 v[78:81], v[114:117], v[222:225], v[78:81]
	v_mfma_f32_16x16x32_bf16 v[74:77], v[122:125], v[222:225], v[74:77]
	v_mfma_f32_16x16x32_bf16 v[142:145], v[118:121], v[202:205], v[142:145]
	v_mfma_f32_16x16x32_bf16 v[138:141], v[126:129], v[202:205], v[138:141]
	v_mfma_f32_16x16x32_bf16 v[110:113], v[118:121], v[210:213], v[110:113]
	v_mfma_f32_16x16x32_bf16 v[106:109], v[126:129], v[210:213], v[106:109]
	v_mfma_f32_16x16x32_bf16 v[94:97], v[118:121], v[218:221], v[94:97]
	v_mfma_f32_16x16x32_bf16 v[90:93], v[126:129], v[218:221], v[90:93]
	v_mfma_f32_16x16x32_bf16 v[78:81], v[118:121], v[226:229], v[78:81]
	v_mfma_f32_16x16x32_bf16 v[74:77], v[126:129], v[226:229], v[74:77]
	s_setprio 0
	s_setprio 1
	v_mfma_f32_16x16x32_bf16 v[134:137], v[182:185], v[198:201], v[134:137]
	v_mfma_f32_16x16x32_bf16 v[130:133], v[190:193], v[198:201], v[130:133]
	v_mfma_f32_16x16x32_bf16 v[102:105], v[182:185], v[206:209], v[102:105]
	v_mfma_f32_16x16x32_bf16 v[98:101], v[190:193], v[206:209], v[98:101]
	v_mfma_f32_16x16x32_bf16 v[86:89], v[182:185], v[214:217], v[86:89]
	v_mfma_f32_16x16x32_bf16 v[82:85], v[190:193], v[214:217], v[82:85]
	v_mfma_f32_16x16x32_bf16 v[70:73], v[182:185], v[222:225], v[70:73]
	v_mfma_f32_16x16x32_bf16 v[66:69], v[190:193], v[222:225], v[66:69]
	v_mfma_f32_16x16x32_bf16 v[134:137], v[186:189], v[202:205], v[134:137]
	v_mfma_f32_16x16x32_bf16 v[130:133], v[194:197], v[202:205], v[130:133]
	v_mfma_f32_16x16x32_bf16 v[102:105], v[186:189], v[210:213], v[102:105]
	v_mfma_f32_16x16x32_bf16 v[98:101], v[194:197], v[210:213], v[98:101]
	v_mfma_f32_16x16x32_bf16 v[86:89], v[186:189], v[218:221], v[86:89]
	v_mfma_f32_16x16x32_bf16 v[82:85], v[194:197], v[218:221], v[82:85]
	v_mfma_f32_16x16x32_bf16 v[70:73], v[186:189], v[226:229], v[70:73]
	v_mfma_f32_16x16x32_bf16 v[66:69], v[194:197], v[226:229], v[66:69]
	s_setprio 0
	s_barrier
	s_add_i32 s77, s72, s34
	v_lshl_add_u64 v[174:175], s[0:1], 0, v[148:149]
	s_mov_b32 m0, s77
	ds_read_b128 v[198:201], v179 offset:16384
	ds_read_b128 v[202:205], v179 offset:17408
	ds_read_b128 v[206:209], v179 offset:18432
	ds_read_b128 v[210:213], v179 offset:19456
	ds_read_b128 v[214:217], v179 offset:20480
	ds_read_b128 v[218:221], v179 offset:21504
	ds_read_b128 v[222:225], v179 offset:22528
	ds_read_b128 v[226:229], v179 offset:23552
	global_load_lds_dwordx4 v[174:175], off
	s_add_i32 m0, s77, 0x2000
	s_add_u32 s78, s0, 0x20000
	v_lshl_add_u64 v[230:231], s[0:1], 0, v[152:153]
	s_addc_u32 s79, s1, 0
	s_add_i32 s77, s73, s34
	global_load_lds_dwordx4 v[230:231], off
	v_lshl_add_u64 v[232:233], s[78:79], 0, v[148:149]
	s_mov_b32 m0, s77
	v_lshl_add_u64 v[234:235], s[12:13], 0, v[150:151]
	global_load_lds_dwordx4 v[232:233], off
	v_lshl_add_u64 v[232:233], s[78:79], 0, v[152:153]
	s_add_i32 m0, s77, 0x2000
	s_nop 0
	global_load_lds_dwordx4 v[232:233], off
	v_lshl_add_u64 v[232:233], s[12:13], 0, v[146:147]
	s_mov_b32 m0, s35
	s_nop 0
	global_load_lds_dwordx4 v[232:233], off
	s_mov_b32 m0, s36
	s_nop 0
	global_load_lds_dwordx4 v[234:235], off
	s_waitcnt vmcnt(8)
	s_waitcnt lgkmcnt(0)
	s_barrier
	s_setprio 1
	s_waitcnt lgkmcnt(0)
	v_mfma_f32_16x16x32_bf16 v[62:65], v[114:117], v[198:201], v[62:65]
	v_mfma_f32_16x16x32_bf16 v[58:61], v[122:125], v[198:201], v[58:61]
	v_mfma_f32_16x16x32_bf16 v[46:49], v[114:117], v[206:209], v[46:49]
	v_mfma_f32_16x16x32_bf16 v[42:45], v[122:125], v[206:209], v[42:45]
	v_mfma_f32_16x16x32_bf16 v[30:33], v[114:117], v[214:217], v[30:33]
	v_mfma_f32_16x16x32_bf16 v[26:29], v[122:125], v[214:217], v[26:29]
	v_mfma_f32_16x16x32_bf16 v[14:17], v[114:117], v[222:225], v[14:17]
	v_mfma_f32_16x16x32_bf16 v[10:13], v[122:125], v[222:225], v[10:13]
	v_mfma_f32_16x16x32_bf16 v[62:65], v[118:121], v[202:205], v[62:65]
	v_mfma_f32_16x16x32_bf16 v[58:61], v[126:129], v[202:205], v[58:61]
	v_mfma_f32_16x16x32_bf16 v[46:49], v[118:121], v[210:213], v[46:49]
	v_mfma_f32_16x16x32_bf16 v[42:45], v[126:129], v[210:213], v[42:45]
	v_mfma_f32_16x16x32_bf16 v[30:33], v[118:121], v[218:221], v[30:33]
	v_mfma_f32_16x16x32_bf16 v[26:29], v[126:129], v[218:221], v[26:29]
	v_mfma_f32_16x16x32_bf16 v[14:17], v[118:121], v[226:229], v[14:17]
	v_mfma_f32_16x16x32_bf16 v[10:13], v[126:129], v[226:229], v[10:13]
	s_setprio 0
	s_setprio 1
	v_mfma_f32_16x16x32_bf16 v[54:57], v[182:185], v[198:201], v[54:57]
	v_mfma_f32_16x16x32_bf16 v[50:53], v[190:193], v[198:201], v[50:53]
	v_mfma_f32_16x16x32_bf16 v[38:41], v[182:185], v[206:209], v[38:41]
	v_mfma_f32_16x16x32_bf16 v[34:37], v[190:193], v[206:209], v[34:37]
	v_mfma_f32_16x16x32_bf16 v[22:25], v[182:185], v[214:217], v[22:25]
	v_mfma_f32_16x16x32_bf16 v[18:21], v[190:193], v[214:217], v[18:21]
	v_mfma_f32_16x16x32_bf16 v[6:9], v[182:185], v[222:225], v[6:9]
	v_mfma_f32_16x16x32_bf16 v[2:5], v[190:193], v[222:225], v[2:5]
	v_mfma_f32_16x16x32_bf16 v[54:57], v[186:189], v[202:205], v[54:57]
	v_mfma_f32_16x16x32_bf16 v[50:53], v[194:197], v[202:205], v[50:53]
	v_mfma_f32_16x16x32_bf16 v[38:41], v[186:189], v[210:213], v[38:41]
	v_mfma_f32_16x16x32_bf16 v[34:37], v[194:197], v[210:213], v[34:37]
	v_mfma_f32_16x16x32_bf16 v[22:25], v[186:189], v[218:221], v[22:25]
	v_mfma_f32_16x16x32_bf16 v[18:21], v[194:197], v[218:221], v[18:21]
	v_mfma_f32_16x16x32_bf16 v[6:9], v[186:189], v[226:229], v[6:9]
	v_mfma_f32_16x16x32_bf16 v[2:5], v[194:197], v[226:229], v[2:5]
	s_setprio 0
	s_barrier
	s_add_i32 s77, 0, 0x18000
	s_add_i32 s78, 0, 0x1c000
	v_add_u32_e32 v126, s77, v159
	v_add_u32_e32 v154, s78, v159
	ds_read_b128 v[114:117], v126
	ds_read_b128 v[118:121], v126 offset:1024
	ds_read_b128 v[122:125], v126 offset:2048
	ds_read_b128 v[126:129], v126 offset:3072
	ds_read_b128 v[182:185], v154
	ds_read_b128 v[186:189], v154 offset:1024
	ds_read_b128 v[190:193], v154 offset:2048
	ds_read_b128 v[194:197], v154 offset:3072
	s_add_u32 s12, s12, 0x80000
	s_addc_u32 s13, s13, 0
	s_mov_b32 m0, s37
	v_lshl_add_u64 v[236:237], s[12:13], 0, v[146:147]
	ds_read_b128 v[198:201], v179 offset:32768
	ds_read_b128 v[202:205], v179 offset:33792
	ds_read_b128 v[206:209], v179 offset:34816
	ds_read_b128 v[210:213], v179 offset:35840
	ds_read_b128 v[214:217], v179 offset:36864
	ds_read_b128 v[218:221], v179 offset:37888
	ds_read_b128 v[222:225], v179 offset:38912
	ds_read_b128 v[226:229], v179 offset:39936
	global_load_lds_dwordx4 v[236:237], off
	v_lshl_add_u64 v[236:237], s[12:13], 0, v[150:151]
	s_mov_b32 m0, s38
	s_nop 0
	global_load_lds_dwordx4 v[236:237], off
	s_waitcnt vmcnt(8)
	s_waitcnt lgkmcnt(0)
	s_barrier
	s_setprio 1
	s_waitcnt lgkmcnt(0)
	v_mfma_f32_16x16x32_bf16 v[142:145], v[114:117], v[198:201], v[142:145]
	v_mfma_f32_16x16x32_bf16 v[138:141], v[122:125], v[198:201], v[138:141]
	v_mfma_f32_16x16x32_bf16 v[110:113], v[114:117], v[206:209], v[110:113]
	v_mfma_f32_16x16x32_bf16 v[106:109], v[122:125], v[206:209], v[106:109]
	v_mfma_f32_16x16x32_bf16 v[94:97], v[114:117], v[214:217], v[94:97]
	v_mfma_f32_16x16x32_bf16 v[90:93], v[122:125], v[214:217], v[90:93]
	v_mfma_f32_16x16x32_bf16 v[78:81], v[114:117], v[222:225], v[78:81]
	v_mfma_f32_16x16x32_bf16 v[74:77], v[122:125], v[222:225], v[74:77]
	v_mfma_f32_16x16x32_bf16 v[142:145], v[118:121], v[202:205], v[142:145]
	v_mfma_f32_16x16x32_bf16 v[138:141], v[126:129], v[202:205], v[138:141]
	v_mfma_f32_16x16x32_bf16 v[110:113], v[118:121], v[210:213], v[110:113]
	v_mfma_f32_16x16x32_bf16 v[106:109], v[126:129], v[210:213], v[106:109]
	v_mfma_f32_16x16x32_bf16 v[94:97], v[118:121], v[218:221], v[94:97]
	v_mfma_f32_16x16x32_bf16 v[90:93], v[126:129], v[218:221], v[90:93]
	v_mfma_f32_16x16x32_bf16 v[78:81], v[118:121], v[226:229], v[78:81]
	v_mfma_f32_16x16x32_bf16 v[74:77], v[126:129], v[226:229], v[74:77]
	s_setprio 0
	s_setprio 1
	v_mfma_f32_16x16x32_bf16 v[134:137], v[182:185], v[198:201], v[134:137]
	v_mfma_f32_16x16x32_bf16 v[130:133], v[190:193], v[198:201], v[130:133]
	v_mfma_f32_16x16x32_bf16 v[102:105], v[182:185], v[206:209], v[102:105]
	v_mfma_f32_16x16x32_bf16 v[98:101], v[190:193], v[206:209], v[98:101]
	v_mfma_f32_16x16x32_bf16 v[86:89], v[182:185], v[214:217], v[86:89]
	v_mfma_f32_16x16x32_bf16 v[82:85], v[190:193], v[214:217], v[82:85]
	v_mfma_f32_16x16x32_bf16 v[70:73], v[182:185], v[222:225], v[70:73]
	v_mfma_f32_16x16x32_bf16 v[66:69], v[190:193], v[222:225], v[66:69]
	v_mfma_f32_16x16x32_bf16 v[134:137], v[186:189], v[202:205], v[134:137]
	v_mfma_f32_16x16x32_bf16 v[130:133], v[194:197], v[202:205], v[130:133]
	v_mfma_f32_16x16x32_bf16 v[102:105], v[186:189], v[210:213], v[102:105]
	v_mfma_f32_16x16x32_bf16 v[98:101], v[194:197], v[210:213], v[98:101]
	v_mfma_f32_16x16x32_bf16 v[86:89], v[186:189], v[218:221], v[86:89]
	v_mfma_f32_16x16x32_bf16 v[82:85], v[194:197], v[218:221], v[82:85]
	v_mfma_f32_16x16x32_bf16 v[70:73], v[186:189], v[226:229], v[70:73]
	v_mfma_f32_16x16x32_bf16 v[66:69], v[194:197], v[226:229], v[66:69]
	s_setprio 0
	s_barrier
	s_add_i32 s12, s77, s34
	v_lshl_add_u64 v[174:175], v[174:175], 0, s[52:53]
	s_mov_b32 m0, s12
	ds_read_b128 v[198:201], v179 offset:49152
	ds_read_b128 v[202:205], v179 offset:50176
	ds_read_b128 v[206:209], v179 offset:51200
	ds_read_b128 v[210:213], v179 offset:52224
	ds_read_b128 v[214:217], v179 offset:53248
	ds_read_b128 v[218:221], v179 offset:54272
	ds_read_b128 v[222:225], v179 offset:55296
	ds_read_b128 v[226:229], v179 offset:56320
	global_load_lds_dwordx4 v[174:175], off
	s_add_i32 m0, s12, 0x2000
	s_add_u32 s0, s0, 0x20080
	v_lshl_add_u64 v[174:175], v[230:231], 0, s[52:53]
	s_addc_u32 s1, s1, 0
	s_add_i32 s12, s78, s34
	global_load_lds_dwordx4 v[174:175], off
	v_lshl_add_u64 v[174:175], s[0:1], 0, v[148:149]
	s_mov_b32 m0, s12
	s_nop 0
	global_load_lds_dwordx4 v[174:175], off
	v_lshl_add_u64 v[174:175], s[0:1], 0, v[152:153]
	s_add_i32 m0, s12, 0x2000
	s_nop 0
	global_load_lds_dwordx4 v[174:175], off
	v_lshl_add_u64 v[174:175], v[232:233], 0, s[52:53]
	s_mov_b32 m0, s44
	s_nop 0
	global_load_lds_dwordx4 v[174:175], off
	v_lshl_add_u64 v[174:175], v[234:235], 0, s[52:53]
	s_mov_b32 m0, s45
	s_nop 0
	global_load_lds_dwordx4 v[174:175], off
	s_waitcnt vmcnt(8)
	s_waitcnt lgkmcnt(0)
	s_barrier
	s_setprio 1
	s_waitcnt lgkmcnt(0)
	v_mfma_f32_16x16x32_bf16 v[62:65], v[114:117], v[198:201], v[62:65]
	v_mfma_f32_16x16x32_bf16 v[58:61], v[122:125], v[198:201], v[58:61]
	v_mfma_f32_16x16x32_bf16 v[46:49], v[114:117], v[206:209], v[46:49]
	v_mfma_f32_16x16x32_bf16 v[42:45], v[122:125], v[206:209], v[42:45]
	v_mfma_f32_16x16x32_bf16 v[30:33], v[114:117], v[214:217], v[30:33]
	v_mfma_f32_16x16x32_bf16 v[26:29], v[122:125], v[214:217], v[26:29]
	v_mfma_f32_16x16x32_bf16 v[14:17], v[114:117], v[222:225], v[14:17]
	v_mfma_f32_16x16x32_bf16 v[10:13], v[122:125], v[222:225], v[10:13]
	v_mfma_f32_16x16x32_bf16 v[62:65], v[118:121], v[202:205], v[62:65]
	v_mfma_f32_16x16x32_bf16 v[58:61], v[126:129], v[202:205], v[58:61]
	v_mfma_f32_16x16x32_bf16 v[46:49], v[118:121], v[210:213], v[46:49]
	v_mfma_f32_16x16x32_bf16 v[42:45], v[126:129], v[210:213], v[42:45]
	v_mfma_f32_16x16x32_bf16 v[30:33], v[118:121], v[218:221], v[30:33]
	v_mfma_f32_16x16x32_bf16 v[26:29], v[126:129], v[218:221], v[26:29]
	v_mfma_f32_16x16x32_bf16 v[14:17], v[118:121], v[226:229], v[14:17]
	v_mfma_f32_16x16x32_bf16 v[10:13], v[126:129], v[226:229], v[10:13]
	s_setprio 0
	s_setprio 1
	v_mfma_f32_16x16x32_bf16 v[54:57], v[182:185], v[198:201], v[54:57]
	v_mfma_f32_16x16x32_bf16 v[50:53], v[190:193], v[198:201], v[50:53]
	s_add_i32 s76, s76, 2
	s_add_u32 s70, s70, 0x100
	s_addc_u32 s71, s71, 0
	s_add_u32 s20, s20, 0x100
	s_addc_u32 s21, s21, 0
	s_cmp_gt_u32 s76, 29
	v_mfma_f32_16x16x32_bf16 v[38:41], v[182:185], v[206:209], v[38:41]
	v_mfma_f32_16x16x32_bf16 v[34:37], v[190:193], v[206:209], v[34:37]
	v_mfma_f32_16x16x32_bf16 v[22:25], v[182:185], v[214:217], v[22:25]
	v_mfma_f32_16x16x32_bf16 v[18:21], v[190:193], v[214:217], v[18:21]
	v_mfma_f32_16x16x32_bf16 v[6:9], v[182:185], v[222:225], v[6:9]
	v_mfma_f32_16x16x32_bf16 v[2:5], v[190:193], v[222:225], v[2:5]
	v_mfma_f32_16x16x32_bf16 v[54:57], v[186:189], v[202:205], v[54:57]
	v_mfma_f32_16x16x32_bf16 v[50:53], v[194:197], v[202:205], v[50:53]
	v_mfma_f32_16x16x32_bf16 v[38:41], v[186:189], v[210:213], v[38:41]
	v_mfma_f32_16x16x32_bf16 v[34:37], v[194:197], v[210:213], v[34:37]
	v_mfma_f32_16x16x32_bf16 v[22:25], v[186:189], v[218:221], v[22:25]
	v_mfma_f32_16x16x32_bf16 v[18:21], v[194:197], v[218:221], v[18:21]
	v_mfma_f32_16x16x32_bf16 v[6:9], v[186:189], v[226:229], v[6:9]
	v_mfma_f32_16x16x32_bf16 v[2:5], v[194:197], v[226:229], v[2:5]
	s_setprio 0
	s_barrier
	s_cbranch_scc0 .LBB0_165
	s_and_b64 vcc, exec, s[56:57]
	s_cbranch_vccz .LBB0_168
	s_barrier

.LBB0_497:
	ds_read_b128 v[108:111], v215
	ds_read_b128 v[132:135], v215 offset:1024
	ds_read_b128 v[136:139], v215 offset:2048
	ds_read_b128 v[140:143], v215 offset:3072
	ds_read_b128 v[144:147], v220
	ds_read_b128 v[148:151], v220 offset:1024
	ds_read_b128 v[152:155], v220 offset:2048
	ds_read_b128 v[156:159], v220 offset:3072
	s_add_u32 s48, s8, 0xfff80080
	s_addc_u32 s49, s9, -1
	s_cmp_eq_u32 s65, 28
	s_cselect_b32 s51, s63, s49
	s_cselect_b32 s50, s64, s48
	s_cselect_b32 s49, s13, s47
	s_cselect_b32 s48, s12, s46
	v_lshl_add_u64 v[244:245], s[8:9], 0, v[178:179]
	s_add_i32 m0, s11, 0xc000
	ds_read_b128 v[184:187], v216
	ds_read_b128 v[188:191], v216 offset:1024
	ds_read_b128 v[192:195], v216 offset:2048
	ds_read_b128 v[224:227], v216 offset:3072
	ds_read_b128 v[228:231], v216 offset:4096
	ds_read_b128 v[232:235], v216 offset:5120
	ds_read_b128 v[236:239], v216 offset:6144
	ds_read_b128 v[240:243], v216 offset:7168
	global_load_lds_dwordx4 v[244:245], off
	v_lshl_add_u64 v[244:245], s[8:9], 0, v[180:181]
	s_add_i32 m0, s11, 0xe000
	s_nop 0
	global_load_lds_dwordx4 v[244:245], off
	s_waitcnt vmcnt(8)
	s_waitcnt lgkmcnt(0)
	s_barrier
	s_setprio 1
	s_waitcnt lgkmcnt(0)
	v_mfma_f32_16x16x32_bf16 v[100:103], v[108:111], v[184:187], v[100:103]
	v_mfma_f32_16x16x32_bf16 v[96:99], v[136:139], v[184:187], v[96:99]
	v_mfma_f32_16x16x32_bf16 v[128:131], v[108:111], v[192:195], v[128:131]
	v_mfma_f32_16x16x32_bf16 v[76:79], v[136:139], v[192:195], v[76:79]
	v_mfma_f32_16x16x32_bf16 v[124:127], v[108:111], v[228:231], v[124:127]
	v_mfma_f32_16x16x32_bf16 v[120:123], v[136:139], v[228:231], v[120:123]
	v_mfma_f32_16x16x32_bf16 v[112:115], v[108:111], v[236:239], v[112:115]
	v_mfma_f32_16x16x32_bf16 v[116:119], v[136:139], v[236:239], v[116:119]
	v_mfma_f32_16x16x32_bf16 v[100:103], v[132:135], v[188:191], v[100:103]
	v_mfma_f32_16x16x32_bf16 v[96:99], v[140:143], v[188:191], v[96:99]
	v_mfma_f32_16x16x32_bf16 v[128:131], v[132:135], v[224:227], v[128:131]
	v_mfma_f32_16x16x32_bf16 v[76:79], v[140:143], v[224:227], v[76:79]
	v_mfma_f32_16x16x32_bf16 v[124:127], v[132:135], v[232:235], v[124:127]
	v_mfma_f32_16x16x32_bf16 v[120:123], v[140:143], v[232:235], v[120:123]
	v_mfma_f32_16x16x32_bf16 v[112:115], v[132:135], v[240:243], v[112:115]
	v_mfma_f32_16x16x32_bf16 v[116:119], v[140:143], v[240:243], v[116:119]
	s_setprio 0
	s_setprio 1
	v_mfma_f32_16x16x32_bf16 v[92:95], v[144:147], v[184:187], v[92:95]
	v_mfma_f32_16x16x32_bf16 v[72:75], v[152:155], v[184:187], v[72:75]
	v_mfma_f32_16x16x32_bf16 v[64:67], v[144:147], v[192:195], v[64:67]
	v_mfma_f32_16x16x32_bf16 v[68:71], v[152:155], v[192:195], v[68:71]
	v_mfma_f32_16x16x32_bf16 v[84:87], v[144:147], v[228:231], v[84:87]
	v_mfma_f32_16x16x32_bf16 v[104:107], v[152:155], v[228:231], v[104:107]
	v_mfma_f32_16x16x32_bf16 v[80:83], v[144:147], v[236:239], v[80:83]
	v_mfma_f32_16x16x32_bf16 v[88:91], v[152:155], v[236:239], v[88:91]
	v_mfma_f32_16x16x32_bf16 v[92:95], v[148:151], v[188:191], v[92:95]
	v_mfma_f32_16x16x32_bf16 v[72:75], v[156:159], v[188:191], v[72:75]
	v_mfma_f32_16x16x32_bf16 v[64:67], v[148:151], v[224:227], v[64:67]
	v_mfma_f32_16x16x32_bf16 v[68:71], v[156:159], v[224:227], v[68:71]
	v_mfma_f32_16x16x32_bf16 v[84:87], v[148:151], v[232:235], v[84:87]
	v_mfma_f32_16x16x32_bf16 v[104:107], v[156:159], v[232:235], v[104:107]
	v_mfma_f32_16x16x32_bf16 v[80:83], v[148:151], v[240:243], v[80:83]
	v_mfma_f32_16x16x32_bf16 v[88:91], v[156:159], v[240:243], v[88:91]
	s_setprio 0
	s_barrier
	s_add_i32 s66, s29, s52
	v_lshl_add_u64 v[244:245], s[48:49], 0, v[162:163]
	s_mov_b32 m0, s66
	ds_read_b128 v[184:187], v216 offset:16384
	ds_read_b128 v[188:191], v216 offset:17408
	ds_read_b128 v[192:195], v216 offset:18432
	ds_read_b128 v[224:227], v216 offset:19456
	ds_read_b128 v[228:231], v216 offset:20480
	ds_read_b128 v[232:235], v216 offset:21504
	ds_read_b128 v[236:239], v216 offset:22528
	ds_read_b128 v[240:243], v216 offset:23552
	global_load_lds_dwordx4 v[244:245], off
	s_add_i32 m0, s66, 0x2000
	s_add_u32 s66, s48, 0x20000
	v_lshl_add_u64 v[246:247], s[48:49], 0, v[166:167]
	s_addc_u32 s67, s49, 0
	s_add_i32 s68, s59, s52
	global_load_lds_dwordx4 v[246:247], off
	v_lshl_add_u64 v[248:249], s[66:67], 0, v[162:163]
	s_mov_b32 m0, s68
	v_lshl_add_u64 v[250:251], s[50:51], 0, v[164:165]
	global_load_lds_dwordx4 v[248:249], off
	v_lshl_add_u64 v[248:249], s[66:67], 0, v[166:167]
	s_add_i32 m0, s68, 0x2000
	s_nop 0
	global_load_lds_dwordx4 v[248:249], off
	v_lshl_add_u64 v[248:249], s[50:51], 0, v[160:161]
	s_mov_b32 m0, s11
	s_nop 0
	global_load_lds_dwordx4 v[248:249], off
	s_mov_b32 m0, s33
	s_nop 0
	global_load_lds_dwordx4 v[250:251], off
	s_waitcnt vmcnt(8)
	s_waitcnt lgkmcnt(0)
	s_barrier
	s_setprio 1
	s_waitcnt lgkmcnt(0)
	v_mfma_f32_16x16x32_bf16 v[12:15], v[108:111], v[184:187], v[12:15]
	v_mfma_f32_16x16x32_bf16 v[20:23], v[136:139], v[184:187], v[20:23]
	v_mfma_f32_16x16x32_bf16 v[24:27], v[108:111], v[192:195], v[24:27]
	v_mfma_f32_16x16x32_bf16 v[28:31], v[136:139], v[192:195], v[28:31]
	v_mfma_f32_16x16x32_bf16 v[40:43], v[108:111], v[228:231], v[40:43]
	v_mfma_f32_16x16x32_bf16 v[44:47], v[136:139], v[228:231], v[44:47]
	v_mfma_f32_16x16x32_bf16 v[48:51], v[108:111], v[236:239], v[48:51]
	v_mfma_f32_16x16x32_bf16 v[52:55], v[136:139], v[236:239], v[52:55]
	v_mfma_f32_16x16x32_bf16 v[12:15], v[132:135], v[188:191], v[12:15]
	v_mfma_f32_16x16x32_bf16 v[20:23], v[140:143], v[188:191], v[20:23]
	v_mfma_f32_16x16x32_bf16 v[24:27], v[132:135], v[224:227], v[24:27]
	v_mfma_f32_16x16x32_bf16 v[28:31], v[140:143], v[224:227], v[28:31]
	v_mfma_f32_16x16x32_bf16 v[40:43], v[132:135], v[232:235], v[40:43]
	v_mfma_f32_16x16x32_bf16 v[44:47], v[140:143], v[232:235], v[44:47]
	v_mfma_f32_16x16x32_bf16 v[48:51], v[132:135], v[240:243], v[48:51]
	v_mfma_f32_16x16x32_bf16 v[52:55], v[140:143], v[240:243], v[52:55]
	s_setprio 0
	s_setprio 1
	v_mfma_f32_16x16x32_bf16 v[0:3], v[144:147], v[184:187], v[0:3]
	v_mfma_f32_16x16x32_bf16 v[4:7], v[152:155], v[184:187], v[4:7]
	v_mfma_f32_16x16x32_bf16 v[8:11], v[144:147], v[192:195], v[8:11]
	v_mfma_f32_16x16x32_bf16 v[16:19], v[152:155], v[192:195], v[16:19]
	v_mfma_f32_16x16x32_bf16 v[32:35], v[144:147], v[228:231], v[32:35]
	v_mfma_f32_16x16x32_bf16 v[36:39], v[152:155], v[228:231], v[36:39]
	v_mfma_f32_16x16x32_bf16 v[56:59], v[144:147], v[236:239], v[56:59]
	v_mfma_f32_16x16x32_bf16 v[60:63], v[152:155], v[236:239], v[60:63]
	v_mfma_f32_16x16x32_bf16 v[0:3], v[148:151], v[188:191], v[0:3]
	v_mfma_f32_16x16x32_bf16 v[4:7], v[156:159], v[188:191], v[4:7]
	v_mfma_f32_16x16x32_bf16 v[8:11], v[148:151], v[224:227], v[8:11]
	v_mfma_f32_16x16x32_bf16 v[16:19], v[156:159], v[224:227], v[16:19]
	v_mfma_f32_16x16x32_bf16 v[32:35], v[148:151], v[232:235], v[32:35]
	v_mfma_f32_16x16x32_bf16 v[36:39], v[156:159], v[232:235], v[36:39]
	v_mfma_f32_16x16x32_bf16 v[56:59], v[148:151], v[240:243], v[56:59]
	v_mfma_f32_16x16x32_bf16 v[60:63], v[156:159], v[240:243], v[60:63]
	s_setprio 0
	s_barrier
	s_add_i32 s66, 0, 0x18000
	s_add_i32 s67, 0, 0x1c000
	v_add_u32_e32 v140, s66, v197
	v_add_u32_e32 v156, s67, v197
	ds_read_b128 v[108:111], v140
	ds_read_b128 v[132:135], v140 offset:1024
	ds_read_b128 v[136:139], v140 offset:2048
	ds_read_b128 v[140:143], v140 offset:3072
	ds_read_b128 v[144:147], v156
	ds_read_b128 v[148:151], v156 offset:1024
	ds_read_b128 v[152:155], v156 offset:2048
	ds_read_b128 v[156:159], v156 offset:3072
	s_add_u32 s50, s50, 0x80000
	s_addc_u32 s51, s51, 0
	s_mov_b32 m0, s53
	v_lshl_add_u64 v[252:253], s[50:51], 0, v[160:161]
	ds_read_b128 v[184:187], v216 offset:32768
	ds_read_b128 v[188:191], v216 offset:33792
	ds_read_b128 v[192:195], v216 offset:34816
	ds_read_b128 v[224:227], v216 offset:35840
	ds_read_b128 v[228:231], v216 offset:36864
	ds_read_b128 v[232:235], v216 offset:37888
	ds_read_b128 v[236:239], v216 offset:38912
	ds_read_b128 v[240:243], v216 offset:39936
	global_load_lds_dwordx4 v[252:253], off
	v_lshl_add_u64 v[252:253], s[50:51], 0, v[164:165]
	s_mov_b32 m0, s54
	s_nop 0
	global_load_lds_dwordx4 v[252:253], off
	s_waitcnt vmcnt(8)
	s_waitcnt lgkmcnt(0)
	s_barrier
	s_setprio 1
	s_waitcnt lgkmcnt(0)
	v_mfma_f32_16x16x32_bf16 v[100:103], v[108:111], v[184:187], v[100:103]
	v_mfma_f32_16x16x32_bf16 v[96:99], v[136:139], v[184:187], v[96:99]
	v_mfma_f32_16x16x32_bf16 v[128:131], v[108:111], v[192:195], v[128:131]
	v_mfma_f32_16x16x32_bf16 v[76:79], v[136:139], v[192:195], v[76:79]
	v_mfma_f32_16x16x32_bf16 v[124:127], v[108:111], v[228:231], v[124:127]
	v_mfma_f32_16x16x32_bf16 v[120:123], v[136:139], v[228:231], v[120:123]
	v_mfma_f32_16x16x32_bf16 v[112:115], v[108:111], v[236:239], v[112:115]
	v_mfma_f32_16x16x32_bf16 v[116:119], v[136:139], v[236:239], v[116:119]
	v_mfma_f32_16x16x32_bf16 v[100:103], v[132:135], v[188:191], v[100:103]
	v_mfma_f32_16x16x32_bf16 v[96:99], v[140:143], v[188:191], v[96:99]
	v_mfma_f32_16x16x32_bf16 v[128:131], v[132:135], v[224:227], v[128:131]
	v_mfma_f32_16x16x32_bf16 v[76:79], v[140:143], v[224:227], v[76:79]
	v_mfma_f32_16x16x32_bf16 v[124:127], v[132:135], v[232:235], v[124:127]
	v_mfma_f32_16x16x32_bf16 v[120:123], v[140:143], v[232:235], v[120:123]
	v_mfma_f32_16x16x32_bf16 v[112:115], v[132:135], v[240:243], v[112:115]
	v_mfma_f32_16x16x32_bf16 v[116:119], v[140:143], v[240:243], v[116:119]
	s_setprio 0
	s_setprio 1
	v_mfma_f32_16x16x32_bf16 v[92:95], v[144:147], v[184:187], v[92:95]
	v_mfma_f32_16x16x32_bf16 v[72:75], v[152:155], v[184:187], v[72:75]
	v_mfma_f32_16x16x32_bf16 v[64:67], v[144:147], v[192:195], v[64:67]
	v_mfma_f32_16x16x32_bf16 v[68:71], v[152:155], v[192:195], v[68:71]
	v_mfma_f32_16x16x32_bf16 v[84:87], v[144:147], v[228:231], v[84:87]
	v_mfma_f32_16x16x32_bf16 v[104:107], v[152:155], v[228:231], v[104:107]
	v_mfma_f32_16x16x32_bf16 v[80:83], v[144:147], v[236:239], v[80:83]
	v_mfma_f32_16x16x32_bf16 v[88:91], v[152:155], v[236:239], v[88:91]
	v_mfma_f32_16x16x32_bf16 v[92:95], v[148:151], v[188:191], v[92:95]
	v_mfma_f32_16x16x32_bf16 v[72:75], v[156:159], v[188:191], v[72:75]
	v_mfma_f32_16x16x32_bf16 v[64:67], v[148:151], v[224:227], v[64:67]
	v_mfma_f32_16x16x32_bf16 v[68:71], v[156:159], v[224:227], v[68:71]
	v_mfma_f32_16x16x32_bf16 v[84:87], v[148:151], v[232:235], v[84:87]
	v_mfma_f32_16x16x32_bf16 v[104:107], v[156:159], v[232:235], v[104:107]
	v_mfma_f32_16x16x32_bf16 v[80:83], v[148:151], v[240:243], v[80:83]
	v_mfma_f32_16x16x32_bf16 v[88:91], v[156:159], v[240:243], v[88:91]
	s_setprio 0
	s_barrier
	s_add_i32 s50, s66, s52
	v_lshl_add_u64 v[244:245], v[244:245], 0, s[24:25]
	s_mov_b32 m0, s50
	ds_read_b128 v[184:187], v216 offset:49152
	ds_read_b128 v[188:191], v216 offset:50176
	ds_read_b128 v[192:195], v216 offset:51200
	ds_read_b128 v[224:227], v216 offset:52224
	ds_read_b128 v[228:231], v216 offset:53248
	ds_read_b128 v[232:235], v216 offset:54272
	ds_read_b128 v[236:239], v216 offset:55296
	ds_read_b128 v[240:243], v216 offset:56320
	global_load_lds_dwordx4 v[244:245], off
	s_add_i32 m0, s50, 0x2000
	s_add_u32 s48, s48, 0x20080
	v_lshl_add_u64 v[244:245], v[246:247], 0, s[24:25]
	s_addc_u32 s49, s49, 0
	s_add_i32 s50, s67, s52
	global_load_lds_dwordx4 v[244:245], off
	v_lshl_add_u64 v[244:245], s[48:49], 0, v[162:163]
	s_mov_b32 m0, s50
	s_nop 0
	global_load_lds_dwordx4 v[244:245], off
	v_lshl_add_u64 v[244:245], s[48:49], 0, v[166:167]
	s_add_i32 m0, s50, 0x2000
	s_nop 0
	global_load_lds_dwordx4 v[244:245], off
	v_lshl_add_u64 v[244:245], v[248:249], 0, s[24:25]
	s_mov_b32 m0, s57
	s_nop 0
	global_load_lds_dwordx4 v[244:245], off
	v_lshl_add_u64 v[244:245], v[250:251], 0, s[24:25]
	s_mov_b32 m0, s58
	s_nop 0
	global_load_lds_dwordx4 v[244:245], off
	s_waitcnt vmcnt(8)
	s_waitcnt lgkmcnt(0)
	s_barrier
	s_setprio 1
	s_waitcnt lgkmcnt(0)
	v_mfma_f32_16x16x32_bf16 v[12:15], v[108:111], v[184:187], v[12:15]
	v_mfma_f32_16x16x32_bf16 v[20:23], v[136:139], v[184:187], v[20:23]
	v_mfma_f32_16x16x32_bf16 v[24:27], v[108:111], v[192:195], v[24:27]
	v_mfma_f32_16x16x32_bf16 v[28:31], v[136:139], v[192:195], v[28:31]
	v_mfma_f32_16x16x32_bf16 v[40:43], v[108:111], v[228:231], v[40:43]
	v_mfma_f32_16x16x32_bf16 v[44:47], v[136:139], v[228:231], v[44:47]
	v_mfma_f32_16x16x32_bf16 v[48:51], v[108:111], v[236:239], v[48:51]
	v_mfma_f32_16x16x32_bf16 v[52:55], v[136:139], v[236:239], v[52:55]
	v_mfma_f32_16x16x32_bf16 v[12:15], v[132:135], v[188:191], v[12:15]
	v_mfma_f32_16x16x32_bf16 v[20:23], v[140:143], v[188:191], v[20:23]
	v_mfma_f32_16x16x32_bf16 v[24:27], v[132:135], v[224:227], v[24:27]
	v_mfma_f32_16x16x32_bf16 v[28:31], v[140:143], v[224:227], v[28:31]
	v_mfma_f32_16x16x32_bf16 v[40:43], v[132:135], v[232:235], v[40:43]
	v_mfma_f32_16x16x32_bf16 v[44:47], v[140:143], v[232:235], v[44:47]
	v_mfma_f32_16x16x32_bf16 v[48:51], v[132:135], v[240:243], v[48:51]
	v_mfma_f32_16x16x32_bf16 v[52:55], v[140:143], v[240:243], v[52:55]
	s_setprio 0
	s_setprio 1
	v_mfma_f32_16x16x32_bf16 v[0:3], v[144:147], v[184:187], v[0:3]
	v_mfma_f32_16x16x32_bf16 v[4:7], v[152:155], v[184:187], v[4:7]
	s_add_i32 s65, s65, 2
	s_add_u32 s8, s8, 0x100
	s_addc_u32 s9, s9, 0
	s_add_u32 s46, s46, 0x100
	s_addc_u32 s47, s47, 0
	s_cmp_gt_u32 s65, 29
	v_mfma_f32_16x16x32_bf16 v[8:11], v[144:147], v[192:195], v[8:11]
	v_mfma_f32_16x16x32_bf16 v[16:19], v[152:155], v[192:195], v[16:19]
	v_mfma_f32_16x16x32_bf16 v[32:35], v[144:147], v[228:231], v[32:35]
	v_mfma_f32_16x16x32_bf16 v[36:39], v[152:155], v[228:231], v[36:39]
	v_mfma_f32_16x16x32_bf16 v[56:59], v[144:147], v[236:239], v[56:59]
	v_mfma_f32_16x16x32_bf16 v[60:63], v[152:155], v[236:239], v[60:63]
	v_mfma_f32_16x16x32_bf16 v[0:3], v[148:151], v[188:191], v[0:3]
	v_mfma_f32_16x16x32_bf16 v[4:7], v[156:159], v[188:191], v[4:7]
	v_mfma_f32_16x16x32_bf16 v[8:11], v[148:151], v[224:227], v[8:11]
	v_mfma_f32_16x16x32_bf16 v[16:19], v[156:159], v[224:227], v[16:19]
	v_mfma_f32_16x16x32_bf16 v[32:35], v[148:151], v[232:235], v[32:35]
	v_mfma_f32_16x16x32_bf16 v[36:39], v[156:159], v[232:235], v[36:39]
	v_mfma_f32_16x16x32_bf16 v[56:59], v[148:151], v[240:243], v[56:59]
	v_mfma_f32_16x16x32_bf16 v[60:63], v[156:159], v[240:243], v[60:63]
	s_setprio 0
	s_barrier
	s_cbranch_scc0 .LBB0_497
	s_and_b64 vcc, exec, s[36:37]
	s_cbranch_vccz .LBB0_500
	s_barrier
